# stack3 plus counted waits in OUT (EpiRes<2>) epilogue
# speedup vs baseline: 1.0366x; 1.0065x over previous
.LBB0_996:
	global_load_dword v189, v[130:131], off offset:12
	v_lshl_or_b32 v172, s46, 8, v180
	v_lshlrev_b64 v[130:131], 12, v[168:169]
	v_ashrrev_i32_e32 v173, 31, v172
	v_lshl_add_u64 v[130:131], s[10:11], 0, v[130:131]
	v_lshlrev_b64 v[174:175], 2, v[172:173]
	v_lshl_add_u64 v[208:209], v[130:131], 0, v[174:175]
	global_load_dwordx4 v[192:195], v[208:209], off
	global_load_dwordx4 v[196:199], v[208:209], off offset:64
	global_load_dwordx4 v[200:203], v[208:209], off offset:512
	global_load_dwordx4 v[204:207], v[208:209], off offset:576
	v_lshlrev_b64 v[130:131], 12, v[166:167]
	global_load_dword v188, v[128:129], off offset:12
	v_lshl_add_u64 v[128:129], s[10:11], 0, v[130:131]
	v_lshl_add_u64 v[176:177], v[128:129], 0, v[174:175]
	global_load_dwordx4 v[140:143], v[176:177], off
	global_load_dwordx4 v[136:139], v[176:177], off offset:64
	global_load_dwordx4 v[132:135], v[176:177], off offset:512
	global_load_dwordx4 v[128:131], v[176:177], off offset:576
	v_lshlrev_b64 v[186:187], 11, v[168:169]
	v_and_b32_e32 v210, 64, v184
	v_xor_b32_e32 v191, 16, v184
	v_lshl_add_u64 v[186:187], s[16:17], 0, v[186:187]
	v_add_u32_e32 v213, 64, v210
	v_lshl_add_u64 v[210:211], v[172:173], 1, v[186:187]
	v_cmp_lt_i32_e32 vcc, v191, v213
	v_xor_b32_e32 v212, 32, v184
	v_cmp_lt_i32_e64 s[4:5], v212, v213
	v_cndmask_b32_e32 v186, v184, v191, vcc
	v_lshlrev_b32_e32 v186, 2, v186
	s_waitcnt lgkmcnt(0)
	s_waitcnt vmcnt(9)
	v_fmamk_f32 v187, v189, 0x3b000000, v182
	v_mul_f32_e32 v189, 0x4b800000, v187
	v_cmp_gt_f32_e32 vcc, s71, v187
	s_nop 1
	v_cndmask_b32_e32 v187, v187, v189, vcc
	v_rsq_f32_e32 v187, v187
	v_cndmask_b32_e64 v189, v184, v212, s[4:5]
	v_mul_f32_e32 v191, 0x45800000, v187
	v_cndmask_b32_e32 v212, v187, v191, vcc
	s_waitcnt vmcnt(8)
	v_pk_fma_f32 v[126:127], v[126:127], v[212:213], v[194:195] op_sel_hi:[1,0,1]
	v_pk_fma_f32 v[124:125], v[124:125], v[212:213], v[192:193] op_sel_hi:[1,0,1]
	s_waitcnt vmcnt(7)
	v_pk_fma_f32 v[122:123], v[122:123], v[212:213], v[198:199] op_sel_hi:[1,0,1]
	v_pk_fma_f32 v[120:121], v[120:121], v[212:213], v[196:197] op_sel_hi:[1,0,1]
	s_waitcnt vmcnt(6)
	v_pk_fma_f32 v[118:119], v[118:119], v[212:213], v[202:203] op_sel_hi:[1,0,1]
	v_pk_fma_f32 v[116:117], v[116:117], v[212:213], v[200:201] op_sel_hi:[1,0,1]
	s_waitcnt vmcnt(5)
	v_pk_fma_f32 v[192:193], v[112:113], v[212:213], v[204:205] op_sel_hi:[1,0,1]
	v_mul_f32_e32 v187, v125, v125
	v_mul_f32_e32 v191, v127, v127
	global_store_dwordx4 v[208:209], v[124:127], off
	v_cvt_pk_bf16_f32 v112, v124, v125
	v_cvt_pk_bf16_f32 v113, v126, v127
	v_mul_f32_e32 v125, v121, v121
	v_mul_f32_e32 v127, v123, v123
	v_pk_fma_f32 v[194:195], v[114:115], v[212:213], v[206:207] op_sel_hi:[1,0,1]
	v_mul_f32_e32 v198, v117, v117
	v_mul_f32_e32 v199, v119, v119
	v_fmac_f32_e32 v187, v124, v124
	v_fmac_f32_e32 v191, v126, v126
	v_fmac_f32_e32 v125, v120, v120
	v_fmac_f32_e32 v127, v122, v122
	v_mul_f32_e32 v200, v193, v193
	v_mul_f32_e32 v201, v195, v195
	global_store_dwordx2 v[210:211], v[112:113], off
	v_fmac_f32_e32 v198, v116, v116
	v_fmac_f32_e32 v199, v118, v118
	v_add_f32_e32 v112, v187, v191
	v_add_f32_e32 v113, v125, v127
	v_fmac_f32_e32 v200, v192, v192
	v_fmac_f32_e32 v201, v194, v194
	v_add_f32_e32 v124, v198, v199
	v_add_f32_e32 v112, v112, v113
	v_add_f32_e32 v125, v200, v201
	v_add_f32_e32 v112, v124, v112
	v_add_f32_e32 v112, v125, v112
	ds_bpermute_b32 v113, v186, v112
	v_lshlrev_b32_e32 v187, 2, v189
	v_cvt_pk_bf16_f32 v114, v120, v121
	v_cvt_pk_bf16_f32 v115, v122, v123
	v_cvt_pk_bf16_f32 v196, v116, v117
	s_waitcnt lgkmcnt(0)
	v_add_f32_e32 v112, v112, v113
	ds_bpermute_b32 v113, v187, v112
	v_cvt_pk_bf16_f32 v197, v118, v119
	global_store_dwordx4 v[208:209], v[120:123], off offset:64
	global_store_dwordx2 v[210:211], v[114:115], off offset:32
	global_store_dwordx4 v[208:209], v[116:119], off offset:512
	global_store_dwordx2 v[210:211], v[196:197], off offset:256
	v_cvt_pk_bf16_f32 v114, v192, v193
	v_cvt_pk_bf16_f32 v115, v194, v195
	global_store_dwordx4 v[208:209], v[192:195], off offset:576
	global_store_dwordx2 v[210:211], v[114:115], off offset:288
	s_and_saveexec_b64 s[4:5], s[0:1]
	s_cbranch_execz .LBB0_998
	v_lshl_add_u64 v[114:115], v[168:169], 2, s[20:21]
	s_waitcnt lgkmcnt(0)
	v_add_f32_e32 v112, v112, v113
	global_atomic_add_f32 v[114:115], v112, off
.LBB0_998:
	s_or_b64 exec, exec, s[4:5]
	s_waitcnt lgkmcnt(0)
	v_lshlrev_b64 v[112:113], 12, v[162:163]
	v_lshl_add_u64 v[112:113], s[10:11], 0, v[112:113]
	v_lshl_add_u64 v[168:169], v[172:173], 2, v[112:113]
	global_load_dwordx4 v[124:127], v[168:169], off
	global_load_dwordx4 v[120:123], v[168:169], off offset:64
	global_load_dwordx4 v[116:119], v[168:169], off offset:512
	global_load_dwordx4 v[112:115], v[168:169], off offset:576
	s_nop 0
	global_load_dword v170, v[170:171], off offset:12
	s_waitcnt vmcnt(17)
	v_fmamk_f32 v171, v188, 0x3b000000, v182
	v_mul_f32_e32 v188, 0x4b800000, v171
	v_cmp_gt_f32_e32 vcc, s71, v171
	s_nop 1
	v_cndmask_b32_e32 v171, v171, v188, vcc
	v_rsq_f32_e32 v171, v171
	s_nop 0
	v_mul_f32_e32 v188, 0x45800000, v171
	v_cndmask_b32_e32 v188, v171, v188, vcc
	s_waitcnt vmcnt(16)
	v_pk_fma_f32 v[110:111], v[110:111], v[188:189], v[142:143] op_sel_hi:[1,0,1]
	v_pk_fma_f32 v[108:109], v[108:109], v[188:189], v[140:141] op_sel_hi:[1,0,1]
	v_mul_f32_e32 v141, v111, v111
	v_mul_f32_e32 v140, v109, v109
	v_fmac_f32_e32 v140, v108, v108
	v_fmac_f32_e32 v141, v110, v110
	v_add_f32_e32 v142, v140, v141
	v_lshlrev_b64 v[140:141], 11, v[166:167]
	v_lshl_add_u64 v[140:141], s[16:17], 0, v[140:141]
	global_store_dwordx4 v[176:177], v[108:111], off
	v_lshl_add_u64 v[140:141], v[172:173], 1, v[140:141]
	s_waitcnt vmcnt(16)
	v_pk_fma_f32 v[104:105], v[104:105], v[188:189], v[136:137] op_sel_hi:[1,0,1]
	v_cvt_pk_bf16_f32 v108, v108, v109
	v_cvt_pk_bf16_f32 v109, v110, v111
	global_store_dwordx2 v[140:141], v[108:109], off
	v_pk_fma_f32 v[106:107], v[106:107], v[188:189], v[138:139] op_sel_hi:[1,0,1]
	v_mul_f32_e32 v108, v105, v105
	v_fmac_f32_e32 v108, v104, v104
	v_mul_f32_e32 v109, v107, v107
	global_store_dwordx4 v[176:177], v[104:107], off offset:64
	s_waitcnt vmcnt(17)
	v_pk_fma_f32 v[102:103], v[102:103], v[188:189], v[134:135] op_sel_hi:[1,0,1]
	v_pk_fma_f32 v[100:101], v[100:101], v[188:189], v[132:133] op_sel_hi:[1,0,1]
	v_cvt_pk_bf16_f32 v104, v104, v105
	v_cvt_pk_bf16_f32 v105, v106, v107
	v_fmac_f32_e32 v109, v106, v106
	global_store_dwordx2 v[140:141], v[104:105], off offset:32
	v_mul_f32_e32 v104, v101, v101
	v_mul_f32_e32 v105, v103, v103
	v_add_f32_e32 v108, v108, v109
	v_fmac_f32_e32 v104, v100, v100
	v_fmac_f32_e32 v105, v102, v102
	v_add_f32_e32 v108, v142, v108
	v_add_f32_e32 v104, v104, v105
	v_add_f32_e32 v108, v104, v108
	s_waitcnt vmcnt(17)
	v_pk_fma_f32 v[106:107], v[98:99], v[188:189], v[130:131] op_sel_hi:[1,0,1]
	v_pk_fma_f32 v[104:105], v[96:97], v[188:189], v[128:129] op_sel_hi:[1,0,1]
	v_mul_f32_e32 v97, v107, v107
	v_mul_f32_e32 v96, v105, v105
	v_fmac_f32_e32 v96, v104, v104
	v_fmac_f32_e32 v97, v106, v106
	v_add_f32_e32 v96, v96, v97
	v_add_f32_e32 v98, v96, v108
	ds_bpermute_b32 v99, v186, v98
	v_cvt_pk_bf16_f32 v96, v100, v101
	v_cvt_pk_bf16_f32 v97, v102, v103
	global_store_dwordx4 v[176:177], v[100:103], off offset:512
	global_store_dwordx2 v[140:141], v[96:97], off offset:256
	s_waitcnt lgkmcnt(0)
	v_add_f32_e32 v96, v98, v99
	ds_bpermute_b32 v97, v187, v96
	v_cvt_pk_bf16_f32 v98, v104, v105
	v_cvt_pk_bf16_f32 v99, v106, v107
	global_store_dwordx4 v[176:177], v[104:107], off offset:576
	global_store_dwordx2 v[140:141], v[98:99], off offset:288
	s_and_saveexec_b64 s[4:5], s[0:1]
	s_cbranch_execz .LBB0_1000
	v_lshl_add_u64 v[98:99], v[166:167], 2, s[20:21]
	s_waitcnt lgkmcnt(0)
	v_add_f32_e32 v96, v96, v97
	global_atomic_add_f32 v[98:99], v96, off
.LBB0_1000:
	s_or_b64 exec, exec, s[4:5]
	s_waitcnt lgkmcnt(0)
	v_lshlrev_b64 v[96:97], 12, v[158:159]
	v_lshl_add_u64 v[96:97], s[10:11], 0, v[96:97]
	v_lshl_add_u64 v[128:129], v[172:173], 2, v[96:97]
	global_load_dwordx4 v[108:111], v[128:129], off
	global_load_dwordx4 v[104:107], v[128:129], off offset:64
	global_load_dwordx4 v[100:103], v[128:129], off offset:512
	global_load_dwordx4 v[96:99], v[128:129], off offset:576
	global_load_dword v130, v[164:165], off offset:12
	s_waitcnt vmcnt(13)
	v_fmamk_f32 v131, v170, 0x3b000000, v182
	v_mul_f32_e32 v132, 0x4b800000, v131
	v_cmp_gt_f32_e32 vcc, s71, v131
	s_nop 1
	v_cndmask_b32_e32 v131, v131, v132, vcc
	v_rsq_f32_e32 v131, v131
	s_nop 0
	v_mul_f32_e32 v132, 0x45800000, v131
	v_cndmask_b32_e32 v132, v131, v132, vcc
	v_pk_fma_f32 v[94:95], v[94:95], v[132:133], v[126:127] op_sel_hi:[1,0,1]
	v_pk_fma_f32 v[92:93], v[92:93], v[132:133], v[124:125] op_sel_hi:[1,0,1]
	v_mul_f32_e32 v125, v95, v95
	v_mul_f32_e32 v124, v93, v93
	v_fmac_f32_e32 v124, v92, v92
	v_fmac_f32_e32 v125, v94, v94
	v_add_f32_e32 v126, v124, v125
	v_lshlrev_b64 v[124:125], 11, v[162:163]
	v_lshl_add_u64 v[124:125], s[16:17], 0, v[124:125]
	global_store_dwordx4 v[168:169], v[92:95], off
	v_lshl_add_u64 v[124:125], v[172:173], 1, v[124:125]
	v_pk_fma_f32 v[88:89], v[88:89], v[132:133], v[120:121] op_sel_hi:[1,0,1]
	v_cvt_pk_bf16_f32 v92, v92, v93
	v_cvt_pk_bf16_f32 v93, v94, v95
	global_store_dwordx2 v[124:125], v[92:93], off
	v_pk_fma_f32 v[90:91], v[90:91], v[132:133], v[122:123] op_sel_hi:[1,0,1]
	v_mul_f32_e32 v92, v89, v89
	v_fmac_f32_e32 v92, v88, v88
	v_mul_f32_e32 v93, v91, v91
	global_store_dwordx4 v[168:169], v[88:91], off offset:64
	v_pk_fma_f32 v[86:87], v[86:87], v[132:133], v[118:119] op_sel_hi:[1,0,1]
	v_pk_fma_f32 v[84:85], v[84:85], v[132:133], v[116:117] op_sel_hi:[1,0,1]
	v_cvt_pk_bf16_f32 v88, v88, v89
	v_cvt_pk_bf16_f32 v89, v90, v91
	v_fmac_f32_e32 v93, v90, v90
	global_store_dwordx2 v[124:125], v[88:89], off offset:32
	v_mul_f32_e32 v88, v85, v85
	v_mul_f32_e32 v89, v87, v87
	v_add_f32_e32 v92, v92, v93
	v_fmac_f32_e32 v88, v84, v84
	v_fmac_f32_e32 v89, v86, v86
	v_add_f32_e32 v92, v126, v92
	v_add_f32_e32 v88, v88, v89
	v_add_f32_e32 v92, v88, v92
	v_pk_fma_f32 v[90:91], v[82:83], v[132:133], v[114:115] op_sel_hi:[1,0,1]
	v_pk_fma_f32 v[88:89], v[80:81], v[132:133], v[112:113] op_sel_hi:[1,0,1]
	v_mul_f32_e32 v81, v91, v91
	v_mul_f32_e32 v80, v89, v89
	v_fmac_f32_e32 v80, v88, v88
	v_fmac_f32_e32 v81, v90, v90
	v_add_f32_e32 v80, v80, v81
	v_add_f32_e32 v82, v80, v92
	ds_bpermute_b32 v83, v186, v82
	v_cvt_pk_bf16_f32 v80, v84, v85
	v_cvt_pk_bf16_f32 v81, v86, v87
	global_store_dwordx4 v[168:169], v[84:87], off offset:512
	global_store_dwordx2 v[124:125], v[80:81], off offset:256
	s_waitcnt lgkmcnt(0)
	v_add_f32_e32 v80, v82, v83
	ds_bpermute_b32 v81, v187, v80
	v_cvt_pk_bf16_f32 v82, v88, v89
	v_cvt_pk_bf16_f32 v83, v90, v91
	global_store_dwordx4 v[168:169], v[88:91], off offset:576
	global_store_dwordx2 v[124:125], v[82:83], off offset:288
	s_and_saveexec_b64 s[4:5], s[0:1]
	s_cbranch_execz .LBB0_1002
	v_lshl_add_u64 v[82:83], v[162:163], 2, s[20:21]
	s_waitcnt lgkmcnt(0)
	v_add_f32_e32 v80, v80, v81
	global_atomic_add_f32 v[82:83], v80, off
.LBB0_1002:
	s_or_b64 exec, exec, s[4:5]
	s_waitcnt lgkmcnt(0)
	v_lshlrev_b64 v[80:81], 12, v[156:157]
	v_lshl_add_u64 v[80:81], s[10:11], 0, v[80:81]
	v_lshl_add_u64 v[112:113], v[172:173], 2, v[80:81]
	global_load_dwordx4 v[92:95], v[112:113], off
	global_load_dwordx4 v[88:91], v[112:113], off offset:64
	global_load_dwordx4 v[84:87], v[112:113], off offset:512
	global_load_dwordx4 v[80:83], v[112:113], off offset:576
	global_load_dword v114, v[160:161], off offset:12
	s_waitcnt vmcnt(13)
	v_fmamk_f32 v115, v130, 0x3b000000, v182
	v_mul_f32_e32 v116, 0x4b800000, v115
	v_cmp_gt_f32_e32 vcc, s71, v115
	s_nop 1
	v_cndmask_b32_e32 v115, v115, v116, vcc
	v_rsq_f32_e32 v115, v115
	s_nop 0
	v_mul_f32_e32 v116, 0x45800000, v115
	v_cndmask_b32_e32 v116, v115, v116, vcc
	v_pk_fma_f32 v[78:79], v[78:79], v[116:117], v[110:111] op_sel_hi:[1,0,1]
	v_pk_fma_f32 v[76:77], v[76:77], v[116:117], v[108:109] op_sel_hi:[1,0,1]
	v_mul_f32_e32 v109, v79, v79
	v_mul_f32_e32 v108, v77, v77
	v_fmac_f32_e32 v108, v76, v76
	v_fmac_f32_e32 v109, v78, v78
	v_add_f32_e32 v110, v108, v109
	v_lshlrev_b64 v[108:109], 11, v[158:159]
	v_lshl_add_u64 v[108:109], s[16:17], 0, v[108:109]
	global_store_dwordx4 v[128:129], v[76:79], off
	v_lshl_add_u64 v[108:109], v[172:173], 1, v[108:109]
	v_pk_fma_f32 v[72:73], v[72:73], v[116:117], v[104:105] op_sel_hi:[1,0,1]
	v_cvt_pk_bf16_f32 v76, v76, v77
	v_cvt_pk_bf16_f32 v77, v78, v79
	global_store_dwordx2 v[108:109], v[76:77], off
	v_pk_fma_f32 v[74:75], v[74:75], v[116:117], v[106:107] op_sel_hi:[1,0,1]
	v_mul_f32_e32 v76, v73, v73
	v_fmac_f32_e32 v76, v72, v72
	v_mul_f32_e32 v77, v75, v75
	global_store_dwordx4 v[128:129], v[72:75], off offset:64
	v_pk_fma_f32 v[70:71], v[70:71], v[116:117], v[102:103] op_sel_hi:[1,0,1]
	v_pk_fma_f32 v[68:69], v[68:69], v[116:117], v[100:101] op_sel_hi:[1,0,1]
	v_cvt_pk_bf16_f32 v72, v72, v73
	v_cvt_pk_bf16_f32 v73, v74, v75
	v_fmac_f32_e32 v77, v74, v74
	global_store_dwordx2 v[108:109], v[72:73], off offset:32
	v_mul_f32_e32 v72, v69, v69
	v_mul_f32_e32 v73, v71, v71
	v_add_f32_e32 v76, v76, v77
	v_fmac_f32_e32 v72, v68, v68
	v_fmac_f32_e32 v73, v70, v70
	v_add_f32_e32 v76, v110, v76
	v_add_f32_e32 v72, v72, v73
	v_add_f32_e32 v76, v72, v76
	v_pk_fma_f32 v[74:75], v[66:67], v[116:117], v[98:99] op_sel_hi:[1,0,1]
	v_pk_fma_f32 v[72:73], v[64:65], v[116:117], v[96:97] op_sel_hi:[1,0,1]
	v_mul_f32_e32 v65, v75, v75
	v_mul_f32_e32 v64, v73, v73
	v_fmac_f32_e32 v64, v72, v72
	v_fmac_f32_e32 v65, v74, v74
	v_add_f32_e32 v64, v64, v65
	v_add_f32_e32 v66, v64, v76
	ds_bpermute_b32 v67, v186, v66
	v_cvt_pk_bf16_f32 v64, v68, v69
	v_cvt_pk_bf16_f32 v65, v70, v71
	global_store_dwordx4 v[128:129], v[68:71], off offset:512
	global_store_dwordx2 v[108:109], v[64:65], off offset:256
	s_waitcnt lgkmcnt(0)
	v_add_f32_e32 v64, v66, v67
	ds_bpermute_b32 v65, v187, v64
	v_cvt_pk_bf16_f32 v66, v72, v73
	v_cvt_pk_bf16_f32 v67, v74, v75
	global_store_dwordx4 v[128:129], v[72:75], off offset:576
	global_store_dwordx2 v[108:109], v[66:67], off offset:288
	s_and_saveexec_b64 s[4:5], s[0:1]
	s_cbranch_execz .LBB0_1004
	v_lshl_add_u64 v[66:67], v[158:159], 2, s[20:21]
	s_waitcnt lgkmcnt(0)
	v_add_f32_e32 v64, v64, v65
	global_atomic_add_f32 v[66:67], v64, off
.LBB0_1004:
	s_or_b64 exec, exec, s[4:5]
	v_or_b32_e32 v96, 16, v156
	v_ashrrev_i32_e32 v97, 31, v96
	s_waitcnt lgkmcnt(0)
	v_lshlrev_b64 v[64:65], 12, v[96:97]
	v_lshl_add_u64 v[98:99], s[10:11], 0, v[64:65]
	v_lshl_add_u64 v[64:65], v[172:173], 2, v[98:99]
	global_load_dwordx4 v[76:79], v[64:65], off
	global_load_dwordx4 v[72:75], v[64:65], off offset:64
	global_load_dwordx4 v[68:71], v[64:65], off offset:512
	s_nop 0
	global_load_dwordx4 v[64:67], v[64:65], off offset:576
	v_lshl_add_u64 v[100:101], v[96:97], 4, s[22:23]
	global_load_dword v100, v[100:101], off offset:12
	s_waitcnt vmcnt(13)
	v_fmamk_f32 v101, v114, 0x3b000000, v182
	v_mul_f32_e32 v102, 0x4b800000, v101
	v_cmp_gt_f32_e32 vcc, s71, v101
	s_nop 1
	v_cndmask_b32_e32 v101, v101, v102, vcc
	v_rsq_f32_e32 v101, v101
	s_nop 0
	v_mul_f32_e32 v102, 0x45800000, v101
	v_cndmask_b32_e32 v102, v101, v102, vcc
	v_pk_fma_f32 v[62:63], v[62:63], v[102:103], v[94:95] op_sel_hi:[1,0,1]
	v_pk_fma_f32 v[60:61], v[60:61], v[102:103], v[92:93] op_sel_hi:[1,0,1]
	v_mul_f32_e32 v93, v63, v63
	v_mul_f32_e32 v92, v61, v61
	v_fmac_f32_e32 v92, v60, v60
	v_fmac_f32_e32 v93, v62, v62
	v_add_f32_e32 v94, v92, v93
	v_lshlrev_b64 v[92:93], 11, v[156:157]
	v_lshl_add_u64 v[92:93], s[16:17], 0, v[92:93]
	global_store_dwordx4 v[112:113], v[60:63], off
	v_lshl_add_u64 v[92:93], v[172:173], 1, v[92:93]
	v_pk_fma_f32 v[56:57], v[56:57], v[102:103], v[88:89] op_sel_hi:[1,0,1]
	v_cvt_pk_bf16_f32 v60, v60, v61
	v_cvt_pk_bf16_f32 v61, v62, v63
	global_store_dwordx2 v[92:93], v[60:61], off
	v_pk_fma_f32 v[58:59], v[58:59], v[102:103], v[90:91] op_sel_hi:[1,0,1]
	v_mul_f32_e32 v60, v57, v57
	v_fmac_f32_e32 v60, v56, v56
	v_mul_f32_e32 v61, v59, v59
	global_store_dwordx4 v[112:113], v[56:59], off offset:64
	v_pk_fma_f32 v[54:55], v[54:55], v[102:103], v[86:87] op_sel_hi:[1,0,1]
	v_pk_fma_f32 v[52:53], v[52:53], v[102:103], v[84:85] op_sel_hi:[1,0,1]
	v_cvt_pk_bf16_f32 v56, v56, v57
	v_cvt_pk_bf16_f32 v57, v58, v59
	v_fmac_f32_e32 v61, v58, v58
	global_store_dwordx2 v[92:93], v[56:57], off offset:32
	v_mul_f32_e32 v56, v53, v53
	v_mul_f32_e32 v57, v55, v55
	v_add_f32_e32 v60, v60, v61
	v_fmac_f32_e32 v56, v52, v52
	v_fmac_f32_e32 v57, v54, v54
	v_add_f32_e32 v60, v94, v60
	v_add_f32_e32 v56, v56, v57
	v_add_f32_e32 v60, v56, v60
	v_pk_fma_f32 v[58:59], v[50:51], v[102:103], v[82:83] op_sel_hi:[1,0,1]
	v_pk_fma_f32 v[56:57], v[48:49], v[102:103], v[80:81] op_sel_hi:[1,0,1]
	v_mul_f32_e32 v49, v59, v59
	v_mul_f32_e32 v48, v57, v57
	v_fmac_f32_e32 v48, v56, v56
	v_fmac_f32_e32 v49, v58, v58
	v_add_f32_e32 v48, v48, v49
	v_add_f32_e32 v50, v48, v60
	ds_bpermute_b32 v51, v186, v50
	v_cvt_pk_bf16_f32 v48, v52, v53
	v_cvt_pk_bf16_f32 v49, v54, v55
	global_store_dwordx4 v[112:113], v[52:55], off offset:512
	global_store_dwordx2 v[92:93], v[48:49], off offset:256
	s_waitcnt lgkmcnt(0)
	v_add_f32_e32 v48, v50, v51
	ds_bpermute_b32 v49, v187, v48
	v_cvt_pk_bf16_f32 v50, v56, v57
	v_cvt_pk_bf16_f32 v51, v58, v59
	global_store_dwordx4 v[112:113], v[56:59], off offset:576
	global_store_dwordx2 v[92:93], v[50:51], off offset:288
	s_and_saveexec_b64 s[4:5], s[0:1]
	s_cbranch_execz .LBB0_1006
	v_lshl_add_u64 v[50:51], v[156:157], 2, s[20:21]
	s_waitcnt lgkmcnt(0)
	v_add_f32_e32 v48, v48, v49
	global_atomic_add_f32 v[50:51], v48, off
.LBB0_1006:
	s_or_b64 exec, exec, s[4:5]
	v_or_b32_e32 v80, 32, v156
	v_ashrrev_i32_e32 v81, 31, v80
	s_waitcnt lgkmcnt(0)
	v_lshlrev_b64 v[48:49], 12, v[80:81]
	v_lshl_add_u64 v[48:49], s[10:11], 0, v[48:49]
	v_lshl_add_u64 v[82:83], v[48:49], 0, v[174:175]
	global_load_dwordx4 v[60:63], v[82:83], off
	global_load_dwordx4 v[56:59], v[82:83], off offset:64
	global_load_dwordx4 v[52:55], v[82:83], off offset:512
	global_load_dwordx4 v[48:51], v[82:83], off offset:576
	v_lshl_add_u64 v[84:85], v[80:81], 4, s[22:23]
	global_load_dword v84, v[84:85], off offset:12
	s_waitcnt vmcnt(13)
	v_fmamk_f32 v85, v100, 0x3b000000, v182
	v_mul_f32_e32 v86, 0x4b800000, v85
	v_cmp_gt_f32_e32 vcc, s71, v85
	s_nop 1
	v_cndmask_b32_e32 v85, v85, v86, vcc
	v_rsq_f32_e32 v85, v85
	s_nop 0
	v_mul_f32_e32 v86, 0x45800000, v85
	v_cndmask_b32_e32 v86, v85, v86, vcc
	v_pk_fma_f32 v[46:47], v[46:47], v[86:87], v[78:79] op_sel_hi:[1,0,1]
	v_pk_fma_f32 v[44:45], v[44:45], v[86:87], v[76:77] op_sel_hi:[1,0,1]
	v_mul_f32_e32 v77, v47, v47
	v_mul_f32_e32 v76, v45, v45
	v_fmac_f32_e32 v76, v44, v44
	v_fmac_f32_e32 v77, v46, v46
	v_lshlrev_b64 v[78:79], 11, v[96:97]
	v_add_f32_e32 v85, v76, v77
	v_lshl_add_u64 v[76:77], v[98:99], 0, v[174:175]
	v_lshl_add_u64 v[78:79], s[16:17], 0, v[78:79]
	global_store_dwordx4 v[76:77], v[44:47], off
	v_lshl_add_u64 v[78:79], v[172:173], 1, v[78:79]
	v_pk_fma_f32 v[40:41], v[40:41], v[86:87], v[72:73] op_sel_hi:[1,0,1]
	v_cvt_pk_bf16_f32 v44, v44, v45
	v_cvt_pk_bf16_f32 v45, v46, v47
	global_store_dwordx2 v[78:79], v[44:45], off
	v_pk_fma_f32 v[42:43], v[42:43], v[86:87], v[74:75] op_sel_hi:[1,0,1]
	v_mul_f32_e32 v44, v41, v41
	v_fmac_f32_e32 v44, v40, v40
	v_mul_f32_e32 v45, v43, v43
	global_store_dwordx4 v[76:77], v[40:43], off offset:64
	v_pk_fma_f32 v[38:39], v[38:39], v[86:87], v[70:71] op_sel_hi:[1,0,1]
	v_pk_fma_f32 v[36:37], v[36:37], v[86:87], v[68:69] op_sel_hi:[1,0,1]
	v_cvt_pk_bf16_f32 v40, v40, v41
	v_cvt_pk_bf16_f32 v41, v42, v43
	v_fmac_f32_e32 v45, v42, v42
	global_store_dwordx2 v[78:79], v[40:41], off offset:32
	v_mul_f32_e32 v40, v37, v37
	v_mul_f32_e32 v41, v39, v39
	v_add_f32_e32 v44, v44, v45
	v_fmac_f32_e32 v40, v36, v36
	v_fmac_f32_e32 v41, v38, v38
	v_add_f32_e32 v44, v85, v44
	v_add_f32_e32 v40, v40, v41
	v_add_f32_e32 v44, v40, v44
	v_pk_fma_f32 v[42:43], v[34:35], v[86:87], v[66:67] op_sel_hi:[1,0,1]
	v_pk_fma_f32 v[40:41], v[32:33], v[86:87], v[64:65] op_sel_hi:[1,0,1]
	v_mul_f32_e32 v33, v43, v43
	v_mul_f32_e32 v32, v41, v41
	v_fmac_f32_e32 v32, v40, v40
	v_fmac_f32_e32 v33, v42, v42
	v_add_f32_e32 v32, v32, v33
	v_add_f32_e32 v34, v32, v44
	ds_bpermute_b32 v35, v186, v34
	v_cvt_pk_bf16_f32 v32, v36, v37
	v_cvt_pk_bf16_f32 v33, v38, v39
	global_store_dwordx4 v[76:77], v[36:39], off offset:512
	global_store_dwordx2 v[78:79], v[32:33], off offset:256
	s_waitcnt lgkmcnt(0)
	v_add_f32_e32 v32, v34, v35
	ds_bpermute_b32 v33, v187, v32
	v_cvt_pk_bf16_f32 v34, v40, v41
	v_cvt_pk_bf16_f32 v35, v42, v43
	global_store_dwordx4 v[76:77], v[40:43], off offset:576
	global_store_dwordx2 v[78:79], v[34:35], off offset:288
	s_and_saveexec_b64 s[4:5], s[0:1]
	s_cbranch_execz .LBB0_1008
	v_lshl_add_u64 v[34:35], v[96:97], 2, s[20:21]
	s_waitcnt lgkmcnt(0)
	v_add_f32_e32 v32, v32, v33
	global_atomic_add_f32 v[34:35], v32, off
.LBB0_1008:
	s_or_b64 exec, exec, s[4:5]
	v_or_b32_e32 v64, 48, v156
	v_ashrrev_i32_e32 v65, 31, v64
	s_waitcnt lgkmcnt(0)
	v_lshlrev_b64 v[32:33], 12, v[64:65]
	v_lshl_add_u64 v[32:33], s[10:11], 0, v[32:33]
	v_lshl_add_u64 v[66:67], v[32:33], 0, v[174:175]
	global_load_dwordx4 v[44:47], v[66:67], off
	global_load_dwordx4 v[40:43], v[66:67], off offset:64
	global_load_dwordx4 v[36:39], v[66:67], off offset:512
	global_load_dwordx4 v[32:35], v[66:67], off offset:576
	v_lshl_add_u64 v[68:69], v[64:65], 4, s[22:23]
	global_load_dword v68, v[68:69], off offset:12
	s_waitcnt vmcnt(13)
	v_fmamk_f32 v69, v84, 0x3b000000, v182
	v_mul_f32_e32 v70, 0x4b800000, v69
	v_cmp_gt_f32_e32 vcc, s71, v69
	s_nop 1
	v_cndmask_b32_e32 v69, v69, v70, vcc
	v_rsq_f32_e32 v69, v69
	s_nop 0
	v_mul_f32_e32 v70, 0x45800000, v69
	v_cndmask_b32_e32 v70, v69, v70, vcc
	v_pk_fma_f32 v[30:31], v[30:31], v[70:71], v[62:63] op_sel_hi:[1,0,1]
	v_pk_fma_f32 v[28:29], v[28:29], v[70:71], v[60:61] op_sel_hi:[1,0,1]
	v_mul_f32_e32 v61, v31, v31
	v_mul_f32_e32 v60, v29, v29
	v_fmac_f32_e32 v60, v28, v28
	v_fmac_f32_e32 v61, v30, v30
	v_add_f32_e32 v62, v60, v61
	v_lshlrev_b64 v[60:61], 11, v[80:81]
	v_lshl_add_u64 v[60:61], s[16:17], 0, v[60:61]
	global_store_dwordx4 v[82:83], v[28:31], off
	v_lshl_add_u64 v[60:61], v[172:173], 1, v[60:61]
	v_pk_fma_f32 v[24:25], v[24:25], v[70:71], v[56:57] op_sel_hi:[1,0,1]
	v_cvt_pk_bf16_f32 v28, v28, v29
	v_cvt_pk_bf16_f32 v29, v30, v31
	global_store_dwordx2 v[60:61], v[28:29], off
	v_pk_fma_f32 v[26:27], v[26:27], v[70:71], v[58:59] op_sel_hi:[1,0,1]
	v_mul_f32_e32 v28, v25, v25
	v_fmac_f32_e32 v28, v24, v24
	v_mul_f32_e32 v29, v27, v27
	global_store_dwordx4 v[82:83], v[24:27], off offset:64
	v_pk_fma_f32 v[22:23], v[22:23], v[70:71], v[54:55] op_sel_hi:[1,0,1]
	v_pk_fma_f32 v[20:21], v[20:21], v[70:71], v[52:53] op_sel_hi:[1,0,1]
	v_cvt_pk_bf16_f32 v24, v24, v25
	v_cvt_pk_bf16_f32 v25, v26, v27
	v_fmac_f32_e32 v29, v26, v26
	global_store_dwordx2 v[60:61], v[24:25], off offset:32
	v_mul_f32_e32 v24, v21, v21
	v_mul_f32_e32 v25, v23, v23
	v_add_f32_e32 v28, v28, v29
	v_fmac_f32_e32 v24, v20, v20
	v_fmac_f32_e32 v25, v22, v22
	v_add_f32_e32 v28, v62, v28
	v_add_f32_e32 v24, v24, v25
	v_add_f32_e32 v28, v24, v28
	v_pk_fma_f32 v[26:27], v[18:19], v[70:71], v[50:51] op_sel_hi:[1,0,1]
	v_pk_fma_f32 v[24:25], v[16:17], v[70:71], v[48:49] op_sel_hi:[1,0,1]
	v_mul_f32_e32 v17, v27, v27
	v_mul_f32_e32 v16, v25, v25
	v_fmac_f32_e32 v16, v24, v24
	v_fmac_f32_e32 v17, v26, v26
	v_add_f32_e32 v16, v16, v17
	v_add_f32_e32 v18, v16, v28
	ds_bpermute_b32 v19, v186, v18
	v_cvt_pk_bf16_f32 v16, v20, v21
	v_cvt_pk_bf16_f32 v17, v22, v23
	global_store_dwordx4 v[82:83], v[20:23], off offset:512
	global_store_dwordx2 v[60:61], v[16:17], off offset:256
	s_waitcnt lgkmcnt(0)
	v_add_f32_e32 v16, v18, v19
	ds_bpermute_b32 v17, v187, v16
	v_cvt_pk_bf16_f32 v18, v24, v25
	v_cvt_pk_bf16_f32 v19, v26, v27
	global_store_dwordx4 v[82:83], v[24:27], off offset:576
	global_store_dwordx2 v[60:61], v[18:19], off offset:288
	s_and_saveexec_b64 s[4:5], s[0:1]
	s_cbranch_execz .LBB0_1010
	v_lshl_add_u64 v[18:19], v[80:81], 2, s[20:21]
	s_waitcnt lgkmcnt(0)
	v_add_f32_e32 v16, v16, v17
	global_atomic_add_f32 v[18:19], v16, off
.LBB0_1010:
	s_or_b64 exec, exec, s[4:5]
	s_waitcnt vmcnt(8)
	v_fmamk_f32 v16, v68, 0x3b000000, v182
	s_waitcnt lgkmcnt(0)
	v_mul_f32_e32 v17, 0x4b800000, v16
	v_cmp_gt_f32_e32 vcc, s71, v16
	s_nop 1
	v_cndmask_b32_e32 v16, v16, v17, vcc
	v_rsq_f32_e32 v16, v16
	s_nop 0
	v_mul_f32_e32 v17, 0x45800000, v16
	v_cndmask_b32_e32 v16, v16, v17, vcc
	v_pk_fma_f32 v[14:15], v[14:15], v[16:17], v[46:47] op_sel_hi:[1,0,1]
	v_pk_fma_f32 v[12:13], v[12:13], v[16:17], v[44:45] op_sel_hi:[1,0,1]
	v_mul_f32_e32 v18, v15, v15
	v_mul_f32_e32 v17, v13, v13
	v_fmac_f32_e32 v17, v12, v12
	v_fmac_f32_e32 v18, v14, v14
	v_add_f32_e32 v17, v17, v18
	v_lshlrev_b64 v[18:19], 11, v[64:65]
	v_lshl_add_u64 v[18:19], s[16:17], 0, v[18:19]
	global_store_dwordx4 v[66:67], v[12:15], off
	v_lshl_add_u64 v[18:19], v[172:173], 1, v[18:19]
	v_pk_fma_f32 v[8:9], v[8:9], v[16:17], v[40:41] op_sel_hi:[1,0,1]
	v_cvt_pk_bf16_f32 v12, v12, v13
	v_cvt_pk_bf16_f32 v13, v14, v15
	global_store_dwordx2 v[18:19], v[12:13], off
	v_pk_fma_f32 v[10:11], v[10:11], v[16:17], v[42:43] op_sel_hi:[1,0,1]
	v_mul_f32_e32 v12, v9, v9
	v_fmac_f32_e32 v12, v8, v8
	v_mul_f32_e32 v13, v11, v11
	global_store_dwordx4 v[66:67], v[8:11], off offset:64
	v_pk_fma_f32 v[6:7], v[6:7], v[16:17], v[38:39] op_sel_hi:[1,0,1]
	v_pk_fma_f32 v[4:5], v[4:5], v[16:17], v[36:37] op_sel_hi:[1,0,1]
	v_cvt_pk_bf16_f32 v8, v8, v9
	v_cvt_pk_bf16_f32 v9, v10, v11
	v_fmac_f32_e32 v13, v10, v10
	global_store_dwordx2 v[18:19], v[8:9], off offset:32
	v_mul_f32_e32 v8, v5, v5
	v_mul_f32_e32 v9, v7, v7
	v_add_f32_e32 v12, v12, v13
	v_fmac_f32_e32 v8, v4, v4
	v_fmac_f32_e32 v9, v6, v6
	v_add_f32_e32 v12, v17, v12
	v_add_f32_e32 v8, v8, v9
	v_add_f32_e32 v12, v8, v12
	v_pk_fma_f32 v[10:11], v[2:3], v[16:17], v[34:35] op_sel_hi:[1,0,1]
	v_pk_fma_f32 v[8:9], v[0:1], v[16:17], v[32:33] op_sel_hi:[1,0,1]
	v_mul_f32_e32 v1, v11, v11
	v_mul_f32_e32 v0, v9, v9
	v_fmac_f32_e32 v0, v8, v8
	v_fmac_f32_e32 v1, v10, v10
	v_add_f32_e32 v0, v0, v1
	v_add_f32_e32 v2, v0, v12
	ds_bpermute_b32 v3, v186, v2
	v_cvt_pk_bf16_f32 v0, v4, v5
	v_cvt_pk_bf16_f32 v1, v6, v7
	global_store_dwordx4 v[66:67], v[4:7], off offset:512
	global_store_dwordx2 v[18:19], v[0:1], off offset:256
	s_waitcnt lgkmcnt(0)
	v_add_f32_e32 v0, v2, v3
	ds_bpermute_b32 v1, v187, v0
	v_cvt_pk_bf16_f32 v2, v8, v9
	v_cvt_pk_bf16_f32 v3, v10, v11
	global_store_dwordx4 v[66:67], v[8:11], off offset:576
	global_store_dwordx2 v[18:19], v[2:3], off offset:288
	s_and_saveexec_b64 s[4:5], s[0:1]
	s_cbranch_execz .LBB0_1012
	v_lshl_add_u64 v[2:3], v[64:65], 2, s[20:21]
	s_waitcnt lgkmcnt(0)
	v_add_f32_e32 v0, v0, v1
	global_atomic_add_f32 v[2:3], v0, off
